# same design as best (regenerated prologue issue code)
# baseline (speedup 1.0000x reference)
; #define ATT_LAS __attribute__((address_space(3)))
; #define ATT_LDK(dst, buf) do { _Pragma("unroll") for (int d0_ = 0; d0_ < 4; ++d0_) { dst[2 * d0_] = *(const ATT_LAS bf16x8*)((buf) + kfrag + d0_ * 2048); dst[2 * d0_ + 1] = *(const ATT_LAS bf16x8*)((buf) + kfrag + d0_ * 2048 + 512); } } while (0)
; template <bool NOMAX> ...
;         const f32x16 zero16 = {};
;         u32x4 kreg, vreg; bf16x8 kf[8]; f32x16 c0, c1, e0, e1;
;         { const u32x4 k0 = *(const u32x4*)(kg + (size_t)ATT_TROW(0) * PITCH), k1 = *(const u32x4*)(kg + (size_t)ATT_TROW(1) * PITCH);
;           *(ATT_LAS u32x4*)(ATT_KBUF(0) + koff) = k0; *(ATT_LAS u32x4*)(ATT_KBUF(1) + koff) = k1; }
;         __syncthreads();
;         kreg = *(const u32x4*)(kg + (size_t)ATT_TROW(2) * PITCH); vreg = *(const u32x4*)(vg + (size_t)ATT_TROW(0) * PITCH);
;         ATT_LDK(kf, ATT_KBUF(0));
;         c0 = (f32x16){}; c1 = (f32x16){};
; #pragma unroll
;         for (int d0 = 0; d0 < 4; ++d0) { c0 = __builtin_amdgcn_mfma_f32_32x32x16_bf16(kf[2 * d0], qf[d0], c0, 0, 0, 0); c1 = __builtin_amdgcn_mfma_f32_32x32x16_bf16(kf[2 * d0 + 1], qf[d0], c1, 0, 0, 0); }
;         m = NOMAX ? 0.f : rowmax32(c0, c1);
; #pragma unroll
;         for (int r = 0; r < 16; ++r) { e0[r] = __builtin_amdgcn_exp2f(c0[r] - m); e1[r] = __builtin_amdgcn_exp2f(c1[r] - m); }
;         ATT_LDK(kf, ATT_KBUF(1));
;         *(ATT_LAS u32x4*)(ATT_KBUF(2) + koff) = kreg; *(ATT_LAS u32x4*)(ATT_VBUF(0) + voff) = vreg;
;         __syncthreads();
;         u32x4 kregB = kreg, vregB = vreg;
;         kreg = *(const u32x4*)(kg + (size_t)ATT_TROW(3) * PITCH); vreg = *(const u32x4*)(vg + (size_t)ATT_TROW(1) * PITCH);
;         int kb2 = 0;
.Lmk_entry_g:
	v_mov_b32_e32 v202, 0
	v_mov_b32_e32 v124, 0
	v_mov_b32_e32 v204, 0
	v_mov_b32_e32 v205, 0
	v_mov_b32_e32 v208, 0
	v_mov_b32_e32 v209, 0
	v_mov_b32_e32 v0, 0
	v_mov_b32_e32 v1, 0
	v_mov_b32_e32 v2, 0
	v_mov_b32_e32 v3, 0
	v_mov_b32_e32 v4, 0
	v_mov_b32_e32 v5, 0
	v_mov_b32_e32 v6, 0
	v_mov_b32_e32 v7, 0
	v_mov_b32_e32 v8, 0
	v_mov_b32_e32 v9, 0
	v_mov_b32_e32 v10, 0
	v_mov_b32_e32 v11, 0
	v_mov_b32_e32 v12, 0
	v_mov_b32_e32 v13, 0
	v_mov_b32_e32 v14, 0
	v_mov_b32_e32 v15, 0
	v_mov_b32_e32 v16, 0
	v_mov_b32_e32 v17, 0
	v_mov_b32_e32 v18, 0
	v_mov_b32_e32 v19, 0
	v_mov_b32_e32 v20, 0
	v_mov_b32_e32 v21, 0
	v_mov_b32_e32 v22, 0
	v_mov_b32_e32 v23, 0
	v_mov_b32_e32 v24, 0
	v_mov_b32_e32 v25, 0
	v_mov_b32_e32 v26, 0
	v_mov_b32_e32 v27, 0
	v_mov_b32_e32 v28, 0
	v_mov_b32_e32 v29, 0
	v_mov_b32_e32 v30, 0
	v_mov_b32_e32 v31, 0
	s_lshl_b32 s92, s93, 6
	s_add_i32 s84, s27, s92
	v_lshrrev_b32_e32 v116, 6, v192
	v_and_b32_e32 v117, 63, v192
	v_lshrrev_b32_e32 v118, 3, v117
	v_sub_u32_e32 v118, v118, v116
	v_mul_i32_i24_e32 v248, 0x8ff0, v118
	v_and_b32_e32 v118, 3, v116
	v_lshlrev_b32_e32 v118, 4, v118
	v_lshlrev_b32_e32 v119, 3, v116
	v_sub_u32_e32 v118, v118, v119
	v_bfe_u32 v119, v117, 3, 1
	v_bfe_u32 v242, v117, 4, 1
	v_bfe_u32 v243, v117, 5, 1
	v_add_u32_e32 v242, v119, v242
	v_lshl_add_u32 v242, v243, 1, v242
	v_lshl_add_u32 v118, v242, 1, v118
	v_lshrrev_b32_e32 v243, 2, v116
	v_sub_u32_e32 v243, v243, v119
	v_mul_i32_i24_e32 v118, 0x1200, v118
	v_lshl_add_u32 v249, v243, 6, v118
	v_readfirstlane_b32 s100, v116
	s_mov_b64 s[98:99], 0x48000
	s_lshl_b32 s100, s100, 10
	v_add_u32_e32 v253, s35, v231
	v_mad_i64_i32 v[244:245], s[80:81], s30, v215, v[198:199]
	v_ashrrev_i32_e32 v243, 31, v248
	v_mov_b32_e32 v242, v248
	v_lshl_add_u64 v[244:245], v[242:243], 0, v[244:245]
	v_mad_i64_i32 v[246:247], s[80:81], s30, v215, v[200:201]
	v_ashrrev_i32_e32 v243, 31, v249
	v_mov_b32_e32 v242, v249
	v_lshl_add_u64 v[246:247], v[242:243], 0, v[246:247]
	s_add_i32 s71, s71, 4
	s_add_i32 s81, s100, 0x0
	s_mov_b32 m0, s81
	s_nop 0
	global_load_lds_dwordx4 v[244:245], off
	v_lshl_add_u64 v[244:245], v[244:245], 0, s[98:99]
	s_add_i32 s81, s100, 0x2000
	s_mov_b32 m0, s81
	s_nop 0
	global_load_lds_dwordx4 v[244:245], off
	v_lshl_add_u64 v[244:245], v[244:245], 0, s[98:99]
	s_add_i32 s81, s100, 0x4000
	s_mov_b32 m0, s81
	s_nop 0
	global_load_lds_dwordx4 v[244:245], off
	v_lshl_add_u64 v[244:245], v[244:245], 0, s[98:99]
	s_add_i32 s81, s100, 0x6000
	s_mov_b32 m0, s81
	s_nop 0
	global_load_lds_dwordx4 v[246:247], off
	v_lshl_add_u64 v[246:247], v[246:247], 0, s[98:99]
	s_waitcnt vmcnt(0)
	s_waitcnt lgkmcnt(0)
	s_barrier
	s_mov_b32 s96, 3
	s_cmp_lg_u32 s96, 4
	s_cbranch_scc1 .Lgp_ks
	v_mad_i64_i32 v[244:245], s[80:81], s84, v215, v[198:199]
	v_ashrrev_i32_e32 v243, 31, v248
	v_mov_b32_e32 v242, v248
	v_lshl_add_u64 v[244:245], v[242:243], 0, v[244:245]
.Lgp_ks:
	s_and_b32 s80, s96, 3
	s_lshl_b32 s81, s80, 13
	s_cmp_eq_u32 s80, 3
	s_cselect_b32 s81, 0xe000, s81
	s_add_i32 s81, s81, s100
	s_mov_b32 m0, s81
	s_nop 0
	global_load_lds_dwordx4 v[244:245], off
	v_lshl_add_u64 v[244:245], v[244:245], 0, s[98:99]
	s_mov_b32 s96, 1
	s_cmp_lg_u32 s96, 4
	s_cbranch_scc1 .Lgp_vs
	v_mad_i64_i32 v[246:247], s[80:81], s84, v215, v[200:201]
	v_ashrrev_i32_e32 v243, 31, v249
	v_mov_b32_e32 v242, v249
	v_lshl_add_u64 v[246:247], v[242:243], 0, v[246:247]
.Lgp_vs:
	s_mul_hi_u32 s80, s96, 0x55555556
	s_mul_i32 s80, s80, 3
	s_sub_u32 s80, s96, s80
	s_lshl_b32 s81, s80, 13
	s_cmp_eq_u32 s80, 2
	s_cselect_b32 s81, 0x6000, s81
	s_add_i32 s81, s81, 0x6000
	s_add_i32 s81, s81, s100
	s_mov_b32 m0, s81
	s_nop 0
	global_load_lds_dwordx4 v[246:247], off
	v_lshl_add_u64 v[246:247], v[246:247], 0, s[98:99]
	v_mov_b32_e32 v243, v221
	ds_read_b128 v[128:131], v243
	ds_read_b128 v[132:135], v243 offset:512
	ds_read_b128 v[136:139], v243 offset:2048
	ds_read_b128 v[140:143], v243 offset:2560
	ds_read_b128 v[144:147], v243 offset:4096
	ds_read_b128 v[148:151], v243 offset:4608
	ds_read_b128 v[152:155], v243 offset:6144
	ds_read_b128 v[156:159], v243 offset:6656
	s_waitcnt lgkmcnt(7)
	v_mfma_f32_32x32x16_bf16 v[32:47], v[128:131], v[96:99], 0
	s_waitcnt lgkmcnt(6)
	v_mfma_f32_32x32x16_bf16 v[64:79], v[132:135], v[96:99], 0
	s_waitcnt lgkmcnt(5)
	v_mfma_f32_32x32x16_bf16 v[32:47], v[136:139], v[100:103], v[32:47]
	s_waitcnt lgkmcnt(4)
	v_mfma_f32_32x32x16_bf16 v[64:79], v[140:143], v[100:103], v[64:79]
	s_waitcnt lgkmcnt(3)
	v_mfma_f32_32x32x16_bf16 v[32:47], v[144:147], v[104:107], v[32:47]
	s_waitcnt lgkmcnt(2)
	v_mfma_f32_32x32x16_bf16 v[64:79], v[148:151], v[104:107], v[64:79]
	s_waitcnt lgkmcnt(1)
	v_mfma_f32_32x32x16_bf16 v[32:47], v[152:155], v[108:111], v[32:47]
	s_waitcnt lgkmcnt(0)
	v_mfma_f32_32x32x16_bf16 v[64:79], v[156:159], v[108:111], v[64:79]
	v_add_u32_e32 v243, 0x2000, v221
	ds_read_b128 v[128:131], v243
	ds_read_b128 v[132:135], v243 offset:512
	ds_read_b128 v[136:139], v243 offset:2048
	ds_read_b128 v[140:143], v243 offset:2560
	ds_read_b128 v[144:147], v243 offset:4096
	ds_read_b128 v[148:151], v243 offset:4608
	ds_read_b128 v[152:155], v243 offset:6144
	ds_read_b128 v[156:159], v243 offset:6656
	s_nop 2
	v_exp_f32_e32 v32, v32
	v_exp_f32_e32 v33, v33
	v_exp_f32_e32 v34, v34
	v_exp_f32_e32 v35, v35
	v_exp_f32_e32 v36, v36
	v_exp_f32_e32 v37, v37
	v_exp_f32_e32 v38, v38
	v_exp_f32_e32 v39, v39
	v_exp_f32_e32 v40, v40
	v_exp_f32_e32 v41, v41
	v_exp_f32_e32 v42, v42
	v_exp_f32_e32 v43, v43
	v_exp_f32_e32 v44, v44
	v_exp_f32_e32 v45, v45
	v_exp_f32_e32 v46, v46
	v_exp_f32_e32 v47, v47
	v_exp_f32_e32 v64, v64
	v_exp_f32_e32 v65, v65
	v_exp_f32_e32 v66, v66
	v_exp_f32_e32 v67, v67
	v_exp_f32_e32 v68, v68
	v_exp_f32_e32 v69, v69
	v_exp_f32_e32 v70, v70
	v_exp_f32_e32 v71, v71
	v_exp_f32_e32 v72, v72
	v_exp_f32_e32 v73, v73
	v_exp_f32_e32 v74, v74
	v_exp_f32_e32 v75, v75
	v_exp_f32_e32 v76, v76
	v_exp_f32_e32 v77, v77
	v_exp_f32_e32 v78, v78
	v_exp_f32_e32 v79, v79
	s_waitcnt lgkmcnt(0)
	s_barrier
	s_mov_b32 s7, 1
